# phase-0 adaLN weight stream loop unrolled x2 with next-slab loads in flight
# baseline (speedup 1.0000x reference)
.LBB0_37:
	v_and_b32_e32 v8, 0x3ff, v7
	v_lshlrev_b32_e32 v28, 2, v8
	v_lshl_add_u64 v[8:9], s[30:31], 0, v[28:29]
	v_cmp_gt_u32_e64 s[4:5], s82, v7
	s_nop 1
	v_cndmask_b32_e64 v9, v9, v3, s[4:5]
	v_cndmask_b32_e64 v8, v8, v2, s[4:5]
	global_load_dword v8, v[8:9], off
	v_add_u32_e32 v9, 0x100, v7
	v_cmp_lt_u32_e64 s[4:5], s83, v7
	s_or_b64 s[8:9], s[4:5], s[8:9]
	v_lshl_add_u64 v[2:3], v[2:3], 0, s[58:59]
	s_waitcnt vmcnt(0)
	v_mul_f32_e32 v10, 0xbfb8aa3b, v8
	v_exp_f32_e32 v10, v10
	s_nop 0
	v_add_f32_e32 v7, 1.0, v10
	v_rcp_f32_e32 v10, v7
	v_mov_b32_e32 v7, v9
	v_mul_f32_e32 v8, v8, v10
	ds_write_b32 v6, v8
	v_add_u32_e32 v6, 0x400, v6
	s_andn2_b64 exec, exec, s[8:9]
	s_cbranch_execnz .LBB0_37
	s_or_b64 exec, exec, s[8:9]
	v_mul_hi_i32 v2, v4, s84
	v_lshrrev_b32_e32 v3, 31, v2
	v_ashrrev_i32_e32 v2, 4, v2
	v_add_u32_e32 v33, v2, v3
	v_mul_lo_u32 v2, v33, s85
	v_sub_u32_e32 v2, v4, v2
	v_lshlrev_b32_e32 v34, 6, v2
	v_and_b32_e32 v61, 63, v5
	v_lshrrev_b32_e32 v4, 6, v30
	v_or_b32_e32 v2, v61, v34
	v_mul_hi_u32_u24_e32 v5, 0x600000, v4
	v_mul_u32_u24_e32 v4, 0x600000, v4
	v_ashrrev_i32_e32 v3, 31, v2
	v_mad_i64_i32 v[4:5], s[4:5], v33, s86, v[4:5]
	v_lshrrev_b32_e32 v36, 6, v30
	v_lshl_add_u64 v[2:3], v[2:3], 2, v[4:5]
	v_mov_b32_e32 v40, 0
	v_lshl_add_u64 v[38:39], s[12:13], 0, v[2:3]
	v_lshl_add_u32 v28, v36, 10, v37
	s_mov_b64 s[8:9], 0
	v_mov_b32_e32 v41, v40
	v_mov_b32_e32 v42, v40
	v_mov_b32_e32 v43, v40
	v_mov_b32_e32 v44, v40
	v_mov_b32_e32 v45, v40
	v_mov_b32_e32 v46, v40
	v_mov_b32_e32 v47, v40
	v_mov_b32_e32 v35, v40
	s_waitcnt lgkmcnt(0)
	s_barrier
	v_lshl_add_u64 v[110:111], v[38:39], 0, s[8:9]
	v_add_co_u32_e64 v112, s[4:5], s87, v110
	s_nop 1
	v_addc_co_u32_e64 v113, s[4:5], 0, v111, s[4:5]
	v_add_co_u32_e64 v114, s[4:5], s88, v110
	s_nop 1
	v_addc_co_u32_e64 v115, s[4:5], 0, v111, s[4:5]
	v_add_co_u32_e64 v116, s[4:5], s89, v110
	s_nop 1
	global_load_dword v124, v[110:111], off
	v_addc_co_u32_e64 v117, s[4:5], 0, v111, s[4:5]
	v_add_co_u32_e64 v118, s[4:5], s90, v110
	s_nop 1
	v_addc_co_u32_e64 v119, s[4:5], 0, v111, s[4:5]
	v_add_co_u32_e64 v120, s[4:5], s91, v110
	s_nop 1
	v_addc_co_u32_e64 v121, s[4:5], 0, v111, s[4:5]
	v_add_co_u32_e64 v122, s[4:5], s92, v110
	s_nop 1
	v_addc_co_u32_e64 v123, s[4:5], 0, v111, s[4:5]
	v_add_co_u32_e64 v110, s[4:5], s93, v110
	s_nop 1
	v_addc_co_u32_e64 v111, s[4:5], 0, v111, s[4:5]
	global_load_dword v112, v[112:113], off
	global_load_dword v114, v[114:115], off
	global_load_dword v116, v[116:117], off
	global_load_dword v118, v[118:119], off
	global_load_dword v120, v[120:121], off
	global_load_dword v122, v[122:123], off
	global_load_dword v110, v[110:111], off
.LBB0_39:
	s_add_u32 s10, s8, 0x30000
	s_min_u32 s10, s10, 0x5d0000
	s_mov_b32 s11, 0
	v_lshl_add_u64 v[130:131], v[38:39], 0, s[10:11]
	v_add_co_u32_e64 v132, s[4:5], s87, v130
	ds_read_b128 v[10:13], v28
	ds_read_b128 v[6:9], v28 offset:16
	ds_read_b128 v[2:5], v28 offset:4096
	ds_read_b128 v[14:17], v28 offset:4112
	ds_read_b128 v[62:65], v28 offset:8192
	ds_read_b128 v[66:69], v28 offset:8208
	ds_read_b128 v[22:25], v28 offset:12288
	ds_read_b128 v[18:21], v28 offset:12304
	ds_read_b128 v[70:73], v28 offset:16384
	ds_read_b128 v[74:77], v28 offset:16400
	ds_read_b128 v[78:81], v28 offset:20480
	ds_read_b128 v[82:85], v28 offset:20496
	ds_read_b128 v[86:89], v28 offset:24576
	ds_read_b128 v[90:93], v28 offset:24592
	ds_read_b128 v[94:97], v28 offset:28672
	ds_read_b128 v[98:101], v28 offset:28688
	v_addc_co_u32_e64 v133, s[4:5], 0, v131, s[4:5]
	v_add_co_u32_e64 v134, s[4:5], s88, v130
	ds_read_b128 v[102:105], v28 offset:32768
	ds_read_b128 v[106:109], v28 offset:32784
	v_addc_co_u32_e64 v135, s[4:5], 0, v131, s[4:5]
	v_add_co_u32_e64 v136, s[4:5], s89, v130
	global_load_dword v144, v[130:131], off
	s_nop 0
	v_addc_co_u32_e64 v137, s[4:5], 0, v131, s[4:5]
	v_add_co_u32_e64 v138, s[4:5], s90, v130
	s_waitcnt lgkmcnt(14)
	v_mov_b32_e32 v126, v10
	v_addc_co_u32_e64 v139, s[4:5], 0, v131, s[4:5]
	v_add_co_u32_e64 v140, s[4:5], s91, v130
	v_mov_b32_e32 v127, v2
	s_nop 0
	v_addc_co_u32_e64 v141, s[4:5], 0, v131, s[4:5]
	v_add_co_u32_e64 v142, s[4:5], s92, v130
	v_mov_b32_e32 v2, v11
	s_nop 0
	v_addc_co_u32_e64 v143, s[4:5], 0, v131, s[4:5]
	v_add_co_u32_e64 v130, s[4:5], s93, v130
	v_mov_b32_e32 v10, v12
	s_nop 0
	v_addc_co_u32_e64 v131, s[4:5], 0, v131, s[4:5]
	global_load_dword v132, v[132:133], off
	s_nop 0
	global_load_dword v134, v[134:135], off
	s_nop 0
	global_load_dword v136, v[136:137], off
	s_nop 0
	global_load_dword v138, v[138:139], off
	s_nop 0
	global_load_dword v140, v[140:141], off
	s_nop 0
	global_load_dword v142, v[142:143], off
	s_nop 0
	global_load_dword v130, v[130:131], off
	v_mov_b32_e32 v11, v4
	v_mov_b32_e32 v4, v13
	s_waitcnt lgkmcnt(13)
	v_mov_b32_e32 v12, v62
	s_waitcnt lgkmcnt(11)
	v_mov_b32_e32 v13, v22
	v_mov_b32_e32 v22, v63
	v_mov_b32_e32 v62, v64
	v_mov_b32_e32 v63, v24
	v_mov_b32_e32 v24, v65
	s_waitcnt lgkmcnt(9)
	v_mov_b32_e32 v64, v70
	s_waitcnt lgkmcnt(7)
	v_mov_b32_e32 v65, v78
	v_mov_b32_e32 v78, v71
	v_mov_b32_e32 v70, v72
	v_mov_b32_e32 v71, v80
	v_mov_b32_e32 v80, v73
	s_waitcnt lgkmcnt(5)
	v_mov_b32_e32 v72, v86
	s_waitcnt lgkmcnt(3)
	v_mov_b32_e32 v73, v94
	v_mov_b32_e32 v94, v87
	v_mov_b32_e32 v86, v88
	v_mov_b32_e32 v87, v96
	v_mov_b32_e32 v96, v89
	v_mov_b32_e32 v88, v6
	v_mov_b32_e32 v89, v14
	v_mov_b32_e32 v14, v7
	v_mov_b32_e32 v6, v8
	v_mov_b32_e32 v7, v16
	v_mov_b32_e32 v16, v9
	v_mov_b32_e32 v8, v66
	v_mov_b32_e32 v9, v18
	v_mov_b32_e32 v18, v67
	v_mov_b32_e32 v66, v68
	v_mov_b32_e32 v67, v20
	v_mov_b32_e32 v20, v69
	v_mov_b32_e32 v68, v74
	v_mov_b32_e32 v69, v82
	v_mov_b32_e32 v82, v75
	v_mov_b32_e32 v74, v76
	v_mov_b32_e32 v75, v84
	v_mov_b32_e32 v84, v77
	v_mov_b32_e32 v76, v90
	s_waitcnt lgkmcnt(2)
	v_mov_b32_e32 v77, v98
	v_mov_b32_e32 v98, v91
	s_add_u32 s8, s8, 0x30000
	v_mov_b32_e32 v90, v92
	v_mov_b32_e32 v91, v100
	s_addc_u32 s9, s9, 0
	v_mov_b32_e32 v100, v93
	v_add_u32_e32 v28, 32, v28
	s_cmp_eq_u32 s8, 0x600000
	s_waitcnt vmcnt(15)
	v_pk_fma_f32 v[40:41], v[124:125], v[126:127], v[40:41] op_sel_hi:[0,1,1]
	v_pk_fma_f32 v[12:13], v[124:125], v[12:13], v[42:43] op_sel_hi:[0,1,1]
	v_pk_fma_f32 v[42:43], v[124:125], v[64:65], v[44:45] op_sel_hi:[0,1,1]
	v_pk_fma_f32 v[44:45], v[124:125], v[72:73], v[46:47] op_sel_hi:[0,1,1]
	s_waitcnt lgkmcnt(1)
	v_fmac_f32_e32 v35, v124, v102
	s_waitcnt vmcnt(14)
	v_pk_fma_f32 v[2:3], v[112:113], v[2:3], v[40:41] op_sel_hi:[0,1,1]
	v_pk_fma_f32 v[12:13], v[112:113], v[22:23], v[12:13] op_sel_hi:[0,1,1]
	v_pk_fma_f32 v[22:23], v[112:113], v[78:79], v[42:43] op_sel_hi:[0,1,1]
	v_pk_fma_f32 v[40:41], v[112:113], v[94:95], v[44:45] op_sel_hi:[0,1,1]
	v_fmac_f32_e32 v35, v112, v103
	s_waitcnt vmcnt(13)
	v_pk_fma_f32 v[2:3], v[114:115], v[10:11], v[2:3] op_sel_hi:[0,1,1]
	v_pk_fma_f32 v[10:11], v[114:115], v[62:63], v[12:13] op_sel_hi:[0,1,1]
	v_pk_fma_f32 v[12:13], v[114:115], v[70:71], v[22:23] op_sel_hi:[0,1,1]
	v_pk_fma_f32 v[22:23], v[114:115], v[86:87], v[40:41] op_sel_hi:[0,1,1]
	v_fmac_f32_e32 v35, v114, v104
	s_waitcnt vmcnt(12)
	v_pk_fma_f32 v[2:3], v[116:117], v[4:5], v[2:3] op_sel_hi:[0,1,1]
	v_pk_fma_f32 v[4:5], v[116:117], v[24:25], v[10:11] op_sel_hi:[0,1,1]
	v_pk_fma_f32 v[10:11], v[116:117], v[80:81], v[12:13] op_sel_hi:[0,1,1]
	v_pk_fma_f32 v[12:13], v[116:117], v[96:97], v[22:23] op_sel_hi:[0,1,1]
	v_fmac_f32_e32 v35, v116, v105
	s_waitcnt vmcnt(11)
	v_pk_fma_f32 v[2:3], v[118:119], v[88:89], v[2:3] op_sel_hi:[0,1,1]
	v_pk_fma_f32 v[4:5], v[118:119], v[8:9], v[4:5] op_sel_hi:[0,1,1]
	v_pk_fma_f32 v[8:9], v[118:119], v[68:69], v[10:11] op_sel_hi:[0,1,1]
	v_pk_fma_f32 v[10:11], v[118:119], v[76:77], v[12:13] op_sel_hi:[0,1,1]
	s_waitcnt lgkmcnt(0)
	v_fmac_f32_e32 v35, v118, v106
	s_waitcnt vmcnt(10)
	v_pk_fma_f32 v[2:3], v[120:121], v[14:15], v[2:3] op_sel_hi:[0,1,1]
	v_pk_fma_f32 v[4:5], v[120:121], v[18:19], v[4:5] op_sel_hi:[0,1,1]
	v_pk_fma_f32 v[8:9], v[120:121], v[82:83], v[8:9] op_sel_hi:[0,1,1]
	v_pk_fma_f32 v[10:11], v[120:121], v[98:99], v[10:11] op_sel_hi:[0,1,1]
	v_fmac_f32_e32 v35, v120, v107
	s_waitcnt vmcnt(9)
	v_pk_fma_f32 v[2:3], v[122:123], v[6:7], v[2:3] op_sel_hi:[0,1,1]
	v_pk_fma_f32 v[4:5], v[122:123], v[66:67], v[4:5] op_sel_hi:[0,1,1]
	v_pk_fma_f32 v[6:7], v[122:123], v[74:75], v[8:9] op_sel_hi:[0,1,1]
	v_pk_fma_f32 v[8:9], v[122:123], v[90:91], v[10:11] op_sel_hi:[0,1,1]
	v_fmac_f32_e32 v35, v122, v108
	s_waitcnt vmcnt(8)
	v_pk_fma_f32 v[40:41], v[110:111], v[16:17], v[2:3] op_sel_hi:[0,1,1]
	v_pk_fma_f32 v[42:43], v[110:111], v[20:21], v[4:5] op_sel_hi:[0,1,1]
	v_pk_fma_f32 v[44:45], v[110:111], v[84:85], v[6:7] op_sel_hi:[0,1,1]
	v_pk_fma_f32 v[46:47], v[110:111], v[100:101], v[8:9] op_sel_hi:[0,1,1]
	v_fmac_f32_e32 v35, v110, v109
	s_cbranch_scc1 .Lmod_exit
.Lmod_b:
	s_add_u32 s10, s8, 0x30000
	s_min_u32 s10, s10, 0x5d0000
	s_mov_b32 s11, 0
	v_lshl_add_u64 v[110:111], v[38:39], 0, s[10:11]
	v_add_co_u32_e64 v112, s[4:5], s87, v110
	ds_read_b128 v[10:13], v28
	ds_read_b128 v[6:9], v28 offset:16
	ds_read_b128 v[2:5], v28 offset:4096
	ds_read_b128 v[14:17], v28 offset:4112
	ds_read_b128 v[62:65], v28 offset:8192
	ds_read_b128 v[66:69], v28 offset:8208
	ds_read_b128 v[22:25], v28 offset:12288
	ds_read_b128 v[18:21], v28 offset:12304
	ds_read_b128 v[70:73], v28 offset:16384
	ds_read_b128 v[74:77], v28 offset:16400
	ds_read_b128 v[78:81], v28 offset:20480
	ds_read_b128 v[82:85], v28 offset:20496
	ds_read_b128 v[86:89], v28 offset:24576
	ds_read_b128 v[90:93], v28 offset:24592
	ds_read_b128 v[94:97], v28 offset:28672
	ds_read_b128 v[98:101], v28 offset:28688
	v_addc_co_u32_e64 v113, s[4:5], 0, v111, s[4:5]
	v_add_co_u32_e64 v114, s[4:5], s88, v110
	ds_read_b128 v[102:105], v28 offset:32768
	ds_read_b128 v[106:109], v28 offset:32784
	v_addc_co_u32_e64 v115, s[4:5], 0, v111, s[4:5]
	v_add_co_u32_e64 v116, s[4:5], s89, v110
	global_load_dword v124, v[110:111], off
	s_nop 0
	v_addc_co_u32_e64 v117, s[4:5], 0, v111, s[4:5]
	v_add_co_u32_e64 v118, s[4:5], s90, v110
	s_waitcnt lgkmcnt(14)
	v_mov_b32_e32 v126, v10
	v_addc_co_u32_e64 v119, s[4:5], 0, v111, s[4:5]
	v_add_co_u32_e64 v120, s[4:5], s91, v110
	v_mov_b32_e32 v127, v2
	s_nop 0
	v_addc_co_u32_e64 v121, s[4:5], 0, v111, s[4:5]
	v_add_co_u32_e64 v122, s[4:5], s92, v110
	v_mov_b32_e32 v2, v11
	s_nop 0
	v_addc_co_u32_e64 v123, s[4:5], 0, v111, s[4:5]
	v_add_co_u32_e64 v110, s[4:5], s93, v110
	v_mov_b32_e32 v10, v12
	s_nop 0
	v_addc_co_u32_e64 v111, s[4:5], 0, v111, s[4:5]
	global_load_dword v112, v[112:113], off
	s_nop 0
	global_load_dword v114, v[114:115], off
	s_nop 0
	global_load_dword v116, v[116:117], off
	s_nop 0
	global_load_dword v118, v[118:119], off
	s_nop 0
	global_load_dword v120, v[120:121], off
	s_nop 0
	global_load_dword v122, v[122:123], off
	s_nop 0
	global_load_dword v110, v[110:111], off
	v_mov_b32_e32 v11, v4
	v_mov_b32_e32 v4, v13
	s_waitcnt lgkmcnt(13)
	v_mov_b32_e32 v12, v62
	s_waitcnt lgkmcnt(11)
	v_mov_b32_e32 v13, v22
	v_mov_b32_e32 v22, v63
	v_mov_b32_e32 v62, v64
	v_mov_b32_e32 v63, v24
	v_mov_b32_e32 v24, v65
	s_waitcnt lgkmcnt(9)
	v_mov_b32_e32 v64, v70
	s_waitcnt lgkmcnt(7)
	v_mov_b32_e32 v65, v78
	v_mov_b32_e32 v78, v71
	v_mov_b32_e32 v70, v72
	v_mov_b32_e32 v71, v80
	v_mov_b32_e32 v80, v73
	s_waitcnt lgkmcnt(5)
	v_mov_b32_e32 v72, v86
	s_waitcnt lgkmcnt(3)
	v_mov_b32_e32 v73, v94
	v_mov_b32_e32 v94, v87
	v_mov_b32_e32 v86, v88
	v_mov_b32_e32 v87, v96
	v_mov_b32_e32 v96, v89
	v_mov_b32_e32 v88, v6
	v_mov_b32_e32 v89, v14
	v_mov_b32_e32 v14, v7
	v_mov_b32_e32 v6, v8
	v_mov_b32_e32 v7, v16
	v_mov_b32_e32 v16, v9
	v_mov_b32_e32 v8, v66
	v_mov_b32_e32 v9, v18
	v_mov_b32_e32 v18, v67
	v_mov_b32_e32 v66, v68
	v_mov_b32_e32 v67, v20
	v_mov_b32_e32 v20, v69
	v_mov_b32_e32 v68, v74
	v_mov_b32_e32 v69, v82
	v_mov_b32_e32 v82, v75
	v_mov_b32_e32 v74, v76
	v_mov_b32_e32 v75, v84
	v_mov_b32_e32 v84, v77
	v_mov_b32_e32 v76, v90
	s_waitcnt lgkmcnt(2)
	v_mov_b32_e32 v77, v98
	v_mov_b32_e32 v98, v91
	s_add_u32 s8, s8, 0x30000
	v_mov_b32_e32 v90, v92
	v_mov_b32_e32 v91, v100
	s_addc_u32 s9, s9, 0
	v_mov_b32_e32 v100, v93
	v_add_u32_e32 v28, 32, v28
	s_cmp_eq_u32 s8, 0x600000
	s_waitcnt vmcnt(15)
	v_pk_fma_f32 v[40:41], v[144:145], v[126:127], v[40:41] op_sel_hi:[0,1,1]
	v_pk_fma_f32 v[12:13], v[144:145], v[12:13], v[42:43] op_sel_hi:[0,1,1]
	v_pk_fma_f32 v[42:43], v[144:145], v[64:65], v[44:45] op_sel_hi:[0,1,1]
	v_pk_fma_f32 v[44:45], v[144:145], v[72:73], v[46:47] op_sel_hi:[0,1,1]
	s_waitcnt lgkmcnt(1)
	v_fmac_f32_e32 v35, v144, v102
	s_waitcnt vmcnt(14)
	v_pk_fma_f32 v[2:3], v[132:133], v[2:3], v[40:41] op_sel_hi:[0,1,1]
	v_pk_fma_f32 v[12:13], v[132:133], v[22:23], v[12:13] op_sel_hi:[0,1,1]
	v_pk_fma_f32 v[22:23], v[132:133], v[78:79], v[42:43] op_sel_hi:[0,1,1]
	v_pk_fma_f32 v[40:41], v[132:133], v[94:95], v[44:45] op_sel_hi:[0,1,1]
	v_fmac_f32_e32 v35, v132, v103
	s_waitcnt vmcnt(13)
	v_pk_fma_f32 v[2:3], v[134:135], v[10:11], v[2:3] op_sel_hi:[0,1,1]
	v_pk_fma_f32 v[10:11], v[134:135], v[62:63], v[12:13] op_sel_hi:[0,1,1]
	v_pk_fma_f32 v[12:13], v[134:135], v[70:71], v[22:23] op_sel_hi:[0,1,1]
	v_pk_fma_f32 v[22:23], v[134:135], v[86:87], v[40:41] op_sel_hi:[0,1,1]
	v_fmac_f32_e32 v35, v134, v104
	s_waitcnt vmcnt(12)
	v_pk_fma_f32 v[2:3], v[136:137], v[4:5], v[2:3] op_sel_hi:[0,1,1]
	v_pk_fma_f32 v[4:5], v[136:137], v[24:25], v[10:11] op_sel_hi:[0,1,1]
	v_pk_fma_f32 v[10:11], v[136:137], v[80:81], v[12:13] op_sel_hi:[0,1,1]
	v_pk_fma_f32 v[12:13], v[136:137], v[96:97], v[22:23] op_sel_hi:[0,1,1]
	v_fmac_f32_e32 v35, v136, v105
	s_waitcnt vmcnt(11)
	v_pk_fma_f32 v[2:3], v[138:139], v[88:89], v[2:3] op_sel_hi:[0,1,1]
	v_pk_fma_f32 v[4:5], v[138:139], v[8:9], v[4:5] op_sel_hi:[0,1,1]
	v_pk_fma_f32 v[8:9], v[138:139], v[68:69], v[10:11] op_sel_hi:[0,1,1]
	v_pk_fma_f32 v[10:11], v[138:139], v[76:77], v[12:13] op_sel_hi:[0,1,1]
	s_waitcnt lgkmcnt(0)
	v_fmac_f32_e32 v35, v138, v106
	s_waitcnt vmcnt(10)
	v_pk_fma_f32 v[2:3], v[140:141], v[14:15], v[2:3] op_sel_hi:[0,1,1]
	v_pk_fma_f32 v[4:5], v[140:141], v[18:19], v[4:5] op_sel_hi:[0,1,1]
	v_pk_fma_f32 v[8:9], v[140:141], v[82:83], v[8:9] op_sel_hi:[0,1,1]
	v_pk_fma_f32 v[10:11], v[140:141], v[98:99], v[10:11] op_sel_hi:[0,1,1]
	v_fmac_f32_e32 v35, v140, v107
	s_waitcnt vmcnt(9)
	v_pk_fma_f32 v[2:3], v[142:143], v[6:7], v[2:3] op_sel_hi:[0,1,1]
	v_pk_fma_f32 v[4:5], v[142:143], v[66:67], v[4:5] op_sel_hi:[0,1,1]
	v_pk_fma_f32 v[6:7], v[142:143], v[74:75], v[8:9] op_sel_hi:[0,1,1]
	v_pk_fma_f32 v[8:9], v[142:143], v[90:91], v[10:11] op_sel_hi:[0,1,1]
	v_fmac_f32_e32 v35, v142, v108
	s_waitcnt vmcnt(8)
	v_pk_fma_f32 v[40:41], v[130:131], v[16:17], v[2:3] op_sel_hi:[0,1,1]
	v_pk_fma_f32 v[42:43], v[130:131], v[20:21], v[4:5] op_sel_hi:[0,1,1]
	v_pk_fma_f32 v[44:45], v[130:131], v[84:85], v[6:7] op_sel_hi:[0,1,1]
	v_pk_fma_f32 v[46:47], v[130:131], v[100:101], v[8:9] op_sel_hi:[0,1,1]
	v_fmac_f32_e32 v35, v130, v109
	s_cbranch_scc0 .LBB0_39
.Lmod_exit:
	s_waitcnt vmcnt(0)
	v_mul_u32_u24_e32 v2, 0x900, v36
	v_lshlrev_b32_e32 v28, 2, v61
	v_add3_u32 v2, v37, v2, v28
	ds_write2st64_b32 v2, v40, v41 offset0:144 offset1:145
	ds_write2st64_b32 v2, v42, v43 offset0:146 offset1:147
	ds_write2st64_b32 v2, v44, v45 offset0:148 offset1:149
	ds_write2st64_b32 v2, v46, v47 offset0:150 offset1:151
	ds_write_b32 v2, v35 offset:38912
	v_mad_u64_u32 v[2:3], s[4:5], v33, s94, v[34:35]
	v_ashrrev_i32_e32 v35, 31, v34
	v_lshl_or_b32 v4, v36, 8, v28
	v_add_u32_e32 v8, v49, v4
	v_mad_u64_u32 v[4:5], s[4:5], v33, 9, v[36:37]
	v_lshlrev_b64 v[10:11], 2, v[34:35]
	v_or_b32_e32 v2, v61, v2
	v_mad_i64_i32 v[4:5], s[4:5], v4, s87, v[10:11]
	v_ashrrev_i32_e32 v3, 31, v2
	v_lshl_add_u64 v[4:5], v[4:5], 0, v[28:29]
	v_lshl_add_u64 v[2:3], v[2:3], 2, s[14:15]
	v_add_u32_e32 v6, v48, v32
	v_or_b32_e32 v7, 0xffffff00, v30
	v_lshl_add_u64 v[4:5], s[18:19], 0, v[4:5]
	s_mov_b64 s[8:9], 0
	s_waitcnt lgkmcnt(0)
	s_barrier
